# pre-step writes the quantised token vectors straight into the wave's LDS buffer (no global xq write + read back)
# speedup vs baseline: 1.0151x; 1.0096x over previous
; __device__ void phase_gather_u(const Params& p) {
;     ...
;   const int tbase = blockIdx.x * 8 + wid, tstride = gridDim.x * 8;
;   for (int t = tbase; t < T_TOK; t += tstride) {
;     const float* orow = p.out + (size_t)t * DM + lane * 32;
;     float xr[32];
;     float amax = 0.f;
; #pragma unroll
;     for (int q = 0; q < 8; ++q) {
;       f32x4 v = *(const f32x4*)(orow + q * 4);
; #pragma unroll
;       for (int k = 0; k < 4; ++k) { xr[q * 4 + k] = v[k]; amax = fmaxf(amax, fabsf(v[k])); }
;     }
; #pragma unroll
;     for (int o = 32; o > 0; o >>= 1) amax = fmaxf(amax, __shfl_xor(amax, o));
.LBB0_1199:
	s_cmp_lt_i32 s56, 9
	s_cselect_b64 s[4:5], -1, 0
	s_and_b64 s[0:1], s[4:5], s[0:1]
	s_andn2_b64 vcc, exec, s[0:1]
	s_cbranch_vccnz .LBB0_1323
	v_lshl_add_u32 v112, s2, 3, v164
	s_movk_i32 s0, 0x4000
	s_lshl_b32 s68, s96, 3
	v_cmp_gt_i32_e64 s[0:1], s0, v112
	v_mbcnt_lo_u32_b32 v30, -1, 0
	s_and_saveexec_b64 s[4:5], s[0:1]
	s_cbranch_execz .LBB0_1205
	v_mbcnt_hi_u32_b32 v0, -1, v30
	v_and_b32_e32 v1, 64, v0
	v_add_u32_e32 v1, 64, v1
	v_xor_b32_e32 v2, 32, v0
	v_cmp_lt_i32_e32 vcc, v2, v1
	v_ashrrev_i32_e32 v113, 31, v112
	s_mov_b64 s[6:7], 0x17c00000
	v_cndmask_b32_e32 v2, v0, v2, vcc
	v_lshlrev_b32_e32 v31, 2, v2
	v_xor_b32_e32 v2, 16, v0
	v_cmp_lt_i32_e32 vcc, v2, v1
	s_mov_b64 s[8:9], 0x15400000
	s_ashr_i32 s69, s68, 31
	v_cndmask_b32_e32 v2, v0, v2, vcc
	v_lshlrev_b32_e32 v32, 2, v2
	v_xor_b32_e32 v2, 8, v0
	v_cmp_lt_i32_e32 vcc, v2, v1
	v_cmp_eq_u32_e64 s[2:3], 0, v138
	s_lshl_b64 s[10:11], s[68:69], 13
	v_cndmask_b32_e32 v2, v0, v2, vcc
	v_lshlrev_b32_e32 v33, 2, v2
	v_xor_b32_e32 v2, 4, v0
	v_cmp_lt_i32_e32 vcc, v2, v1
	s_mov_b64 s[12:13], 0
	s_mov_b32 s16, 0x42ee0000
	v_cndmask_b32_e32 v2, v0, v2, vcc
	v_lshlrev_b32_e32 v34, 2, v2
	v_xor_b32_e32 v2, 2, v0
	v_cmp_lt_i32_e32 vcc, v2, v1
	s_movk_i32 s17, 0xf0
	s_movk_i32 s18, 0x3fff
	v_cndmask_b32_e32 v2, v0, v2, vcc
	v_lshlrev_b32_e32 v35, 2, v2
	v_xor_b32_e32 v2, 1, v0
	v_cmp_lt_i32_e32 vcc, v2, v1
	v_mov_b32_e32 v37, 15
	v_mov_b32_e32 v38, v112
	v_cndmask_b32_e32 v0, v0, v2, vcc
	v_lshlrev_b32_e32 v36, 2, v0
	v_lshl_add_u64 v[0:1], v[112:113], 2, s[34:35]
	v_lshl_add_u64 v[24:25], v[0:1], 0, s[6:7]
	v_lshlrev_b64 v[0:1], 11, v[112:113]
	v_lshl_or_b32 v0, v138, 5, v0
	v_lshl_add_u64 v[0:1], s[34:35], 0, v[0:1]
	v_lshl_add_u64 v[26:27], v[0:1], 0, s[8:9]
	v_lshlrev_b64 v[0:1], 13, v[112:113]
	v_lshl_or_b32 v0, v138, 7, v0
	s_lshl_b64 s[6:7], s[68:69], 2
	s_lshl_b64 s[8:9], s[68:69], 11
	v_lshl_add_u64 v[28:29], s[30:31], 0, v[0:1]
	v_lshrrev_b32_e32 v64, 6, v139
	v_lshlrev_b32_e32 v64, 14, v64
	v_lshl_add_u32 v64, v138, 5, v64
	v_add_u32_e32 v64, 0x2000, v64
	s_branch .LBB0_1203
.LBB0_1202:
	s_or_b64 exec, exec, s[14:15]
	v_add_u32_e32 v64, 0x800, v64
	v_add_u32_e32 v38, s68, v38
	v_cmp_lt_i32_e32 vcc, s18, v38
	v_lshl_add_u64 v[24:25], v[24:25], 0, s[6:7]
	v_lshl_add_u64 v[26:27], v[26:27], 0, s[8:9]
	s_or_b64 s[12:13], vcc, s[12:13]
	v_lshl_add_u64 v[28:29], v[28:29], 0, s[10:11]
	s_andn2_b64 exec, exec, s[12:13]
	s_cbranch_execz .LBB0_1205
.LBB0_1203:
	global_load_dwordx4 v[40:43], v[28:29], off
	global_load_dwordx4 v[44:47], v[28:29], off offset:16
	global_load_dwordx4 v[20:23], v[28:29], off offset:32
	global_load_dwordx4 v[16:19], v[28:29], off offset:48
	global_load_dwordx4 v[12:15], v[28:29], off offset:64
	global_load_dwordx4 v[8:11], v[28:29], off offset:80
	s_waitcnt lgkmcnt(0)
	global_load_dwordx4 v[4:7], v[28:29], off offset:96
	global_load_dwordx4 v[0:3], v[28:29], off offset:112
	s_waitcnt vmcnt(7)
	v_max3_f32 v39, |v40|, 0, |v41|
	v_max3_f32 v39, v39, |v42|, |v43|
	s_waitcnt vmcnt(6)
	v_max3_f32 v39, v39, |v44|, |v45|
	v_max3_f32 v39, v39, |v46|, |v47|
	s_waitcnt vmcnt(5)
	v_max3_f32 v39, v39, |v20|, |v21|
	v_max3_f32 v39, v39, |v22|, |v23|
	s_waitcnt vmcnt(4)
	v_max3_f32 v39, v39, |v16|, |v17|
	v_max3_f32 v39, v39, |v18|, |v19|
	s_waitcnt vmcnt(3)
	v_max3_f32 v39, v39, |v12|, |v13|
	v_max3_f32 v39, v39, |v14|, |v15|
	s_waitcnt vmcnt(2)
	v_max3_f32 v39, v39, |v8|, |v9|
	v_max3_f32 v39, v39, |v10|, |v11|
	s_waitcnt vmcnt(1)
	v_max3_f32 v39, v39, |v4|, |v5|
	v_max3_f32 v39, v39, |v6|, |v7|
	s_waitcnt vmcnt(0)
	v_max3_f32 v39, v39, |v0|, |v1|
	v_max3_f32 v39, v39, |v2|, |v3|
	ds_bpermute_b32 v48, v31, v39
	s_waitcnt lgkmcnt(0)
	v_max_f32_e32 v48, v48, v48
	v_max_f32_e32 v39, v39, v48
	ds_bpermute_b32 v48, v32, v39
	s_waitcnt lgkmcnt(0)
	v_max_f32_e32 v48, v48, v48
	v_max_f32_e32 v39, v39, v48
	ds_bpermute_b32 v48, v33, v39
	s_waitcnt lgkmcnt(0)
	v_max_f32_e32 v48, v48, v48
	v_max_f32_e32 v39, v39, v48
	ds_bpermute_b32 v48, v34, v39
	s_waitcnt lgkmcnt(0)
	v_max_f32_e32 v48, v48, v48
	v_max_f32_e32 v39, v39, v48
	ds_bpermute_b32 v48, v35, v39
	s_waitcnt lgkmcnt(0)
	v_max_f32_e32 v48, v48, v48
	v_max_f32_e32 v39, v39, v48
	ds_bpermute_b32 v48, v36, v39
	s_waitcnt lgkmcnt(0)
; __device__ void phase_gather_u(const Params& p) {
;     ...
;     const float inv = amax > 0.f ? 119.f / amax : 0.f;
;     u32x4 ph, pl;
; #pragma unroll
;     for (int m = 0; m < 4; ++m) {
;       unsigned wh = 0, wl = 0;
; #pragma unroll
;       for (int j = 0; j < 4; ++j) {
;         const int a_ = __float2int_rn(xr[m * 8 + j] * inv), b_ = __float2int_rn(xr[m * 8 + 4 + j] * inv);
;         const int ah = (a_ + 8) >> 4, bh = (b_ + 8) >> 4;
;         const int al = a_ - 16 * ah, bl = b_ - 16 * bh;
;         wh |= (((unsigned)ah & 0xfu) | (((unsigned)bh & 0xfu) << 4)) << (8 * j);
;         wl |= (((unsigned)al & 0xfu) | (((unsigned)bl & 0xfu) << 4)) << (8 * j);
;       }
	v_max_f32_e32 v48, v48, v48
	v_max_f32_e32 v39, v39, v48
	v_div_scale_f32 v48, s[14:15], v39, v39, s16
	v_rcp_f32_e32 v49, v48
	v_div_scale_f32 v50, vcc, s16, v39, s16
	v_fma_f32 v51, -v48, v49, 1.0
	v_fmac_f32_e32 v49, v51, v49
	v_mul_f32_e32 v51, v50, v49
	v_fma_f32 v52, -v48, v51, v50
	v_fmac_f32_e32 v51, v52, v49
	v_fma_f32 v48, -v48, v51, v50
	v_div_fmas_f32 v48, v48, v49, v51
	v_div_fixup_f32 v48, v48, v39, s16
	v_cmp_lt_f32_e32 vcc, 0, v39
	s_nop 1
	v_cndmask_b32_e32 v48, 0, v48, vcc
	v_mul_f32_e32 v40, v40, v48
	v_mul_f32_e32 v44, v44, v48
	v_mul_f32_e32 v41, v41, v48
	v_mul_f32_e32 v45, v45, v48
	v_mul_f32_e32 v42, v42, v48
	v_mul_f32_e32 v46, v46, v48
	v_mul_f32_e32 v43, v43, v48
	v_mul_f32_e32 v47, v47, v48
	v_mul_f32_e32 v20, v20, v48
	v_mul_f32_e32 v16, v16, v48
	v_mul_f32_e32 v21, v21, v48
	v_mul_f32_e32 v17, v17, v48
	v_mul_f32_e32 v22, v22, v48
	v_mul_f32_e32 v18, v18, v48
	v_rndne_f32_e32 v40, v40
	v_rndne_f32_e32 v44, v44
	v_rndne_f32_e32 v41, v41
	v_rndne_f32_e32 v45, v45
	v_rndne_f32_e32 v42, v42
	v_rndne_f32_e32 v46, v46
	v_rndne_f32_e32 v43, v43
	v_rndne_f32_e32 v47, v47
	v_rndne_f32_e32 v20, v20
	v_rndne_f32_e32 v16, v16
	v_rndne_f32_e32 v21, v21
	v_rndne_f32_e32 v17, v17
	v_rndne_f32_e32 v22, v22
	v_rndne_f32_e32 v18, v18
	v_cvt_i32_f32_e32 v40, v40
	v_cvt_i32_f32_e32 v44, v44
	v_cvt_i32_f32_e32 v41, v41
	v_cvt_i32_f32_e32 v45, v45
	v_cvt_i32_f32_e32 v42, v42
	v_cvt_i32_f32_e32 v46, v46
	v_cvt_i32_f32_e32 v43, v43
	v_cvt_i32_f32_e32 v47, v47
	v_cvt_i32_f32_e32 v20, v20
	v_cvt_i32_f32_e32 v16, v16
	v_cvt_i32_f32_e32 v21, v21
	v_cvt_i32_f32_e32 v17, v17
	v_cvt_i32_f32_e32 v22, v22
	v_cvt_i32_f32_e32 v18, v18
	v_add_u32_e32 v49, 8, v40
	v_add_u32_e32 v50, 8, v44
	v_lshlrev_b32_e32 v44, 4, v44
	v_add_u32_e32 v51, 8, v41
	v_add_u32_e32 v52, 8, v45
	v_and_b32_e32 v41, 15, v41
	v_lshlrev_b32_e32 v45, 4, v45
	v_add_u32_e32 v53, 8, v42
	v_add_u32_e32 v54, 8, v46
	v_and_b32_e32 v42, 15, v42
	v_lshlrev_b32_e32 v46, 4, v46
	v_add_u32_e32 v55, 8, v43
	v_add_u32_e32 v56, 8, v47
	v_and_b32_sdwa v43, v43, v37 dst_sel:BYTE_3 dst_unused:UNUSED_PAD src0_sel:DWORD src1_sel:DWORD
	v_add_u32_e32 v57, 8, v20
	v_add_u32_e32 v58, 8, v16
	v_lshlrev_b32_e32 v16, 4, v16
	v_add_u32_e32 v59, 8, v21
	v_add_u32_e32 v60, 8, v17
	v_and_b32_e32 v21, 15, v21
	v_lshlrev_b32_e32 v17, 4, v17
	v_add_u32_e32 v61, 8, v22
	v_add_u32_e32 v62, 8, v18
	v_and_b32_e32 v22, 15, v22
	v_lshlrev_b32_e32 v18, 4, v18
	v_bfe_u32 v49, v49, 4, 4
	v_and_b32_e32 v44, 0xf0, v44
	v_lshrrev_b32_e32 v51, 4, v51
	v_and_b32_e32 v52, 0xf0, v52
	v_and_or_b32 v41, v45, s17, v41
	v_lshrrev_b32_e32 v45, 4, v53
	v_and_b32_e32 v53, 0xf0, v54
	v_and_or_b32 v42, v46, s17, v42
	v_lshrrev_b32_e32 v46, 4, v55
	v_and_b32_e32 v54, 0xf0, v56
	v_lshl_or_b32 v43, v47, 28, v43
	v_bfe_u32 v47, v57, 4, 4
	v_and_b32_e32 v16, 0xf0, v16
	v_and_or_b32 v17, v17, s17, v21
	v_lshrrev_b32_e32 v21, 4, v61
	v_and_b32_e32 v57, 0xf0, v62
	v_and_or_b32 v18, v18, s17, v22
	v_and_or_b32 v22, v50, s17, v49
	v_and_or_b32 v40, v40, 15, v44
	v_and_or_b32 v44, v51, 15, v52
	v_and_or_b32 v46, v46, 15, v54
	v_and_or_b32 v16, v20, 15, v16
	v_and_or_b32 v21, v21, 15, v57
	v_lshl_or_b32 v22, v44, 8, v22
	v_lshlrev_b32_e32 v44, 24, v46
	v_lshl_or_b32 v46, v17, 8, v16
	v_lshlrev_b32_e32 v17, 16, v21
	v_mul_f32_e32 v21, v23, v48
	v_rndne_f32_e32 v21, v21
	v_mul_f32_e32 v19, v19, v48
	v_cvt_i32_f32_e32 v21, v21
	v_rndne_f32_e32 v19, v19
	v_mul_f32_e32 v12, v12, v48
	v_mul_f32_e32 v8, v8, v48
	v_cvt_i32_f32_e32 v19, v19
	v_rndne_f32_e32 v12, v12
	v_rndne_f32_e32 v8, v8
	v_and_or_b32 v45, v45, 15, v53
	v_cvt_i32_f32_e32 v12, v12
	v_cvt_i32_f32_e32 v8, v8
	v_mul_f32_e32 v13, v13, v48
	v_mul_f32_e32 v9, v9, v48
	v_lshl_or_b32 v40, v41, 8, v40
	v_lshlrev_b32_e32 v41, 16, v45
	v_rndne_f32_e32 v13, v13
	v_rndne_f32_e32 v9, v9
	v_or3_b32 v16, v22, v41, v44
	v_add_u32_e32 v22, 8, v21
	v_and_b32_sdwa v21, v21, v37 dst_sel:BYTE_3 dst_unused:UNUSED_PAD src0_sel:DWORD src1_sel:DWORD
	v_cvt_i32_f32_e32 v13, v13
	v_cvt_i32_f32_e32 v9, v9
	v_lshlrev_b32_e32 v18, 16, v18
	v_add_u32_e32 v23, 8, v19
	v_lshl_or_b32 v19, v19, 28, v21
	v_or3_b32 v21, v46, v18, v19
	v_add_u32_e32 v18, 8, v12
	v_add_u32_e32 v19, 8, v8
	v_lshlrev_b32_e32 v8, 4, v8
	v_bfe_u32 v18, v18, 4, 4
	v_and_b32_e32 v8, 0xf0, v8
	v_and_or_b32 v18, v19, s17, v18
	v_and_or_b32 v8, v12, 15, v8
	v_add_u32_e32 v12, 8, v13
	v_add_u32_e32 v19, 8, v9
	v_and_b32_e32 v13, 15, v13
	v_lshlrev_b32_e32 v9, 4, v9
	v_and_or_b32 v9, v9, s17, v13
	v_mul_f32_e32 v13, v14, v48
	v_mul_f32_e32 v10, v10, v48
	v_rndne_f32_e32 v13, v13
	v_rndne_f32_e32 v10, v10
	v_cvt_i32_f32_e32 v13, v13
	v_cvt_i32_f32_e32 v10, v10
	v_lshl_or_b32 v8, v9, 8, v8
	v_mul_f32_e32 v11, v11, v48
	v_add_u32_e32 v9, 8, v13
	v_add_u32_e32 v14, 8, v10
	v_and_b32_e32 v13, 15, v13
	v_lshlrev_b32_e32 v10, 4, v10
	v_and_or_b32 v10, v10, s17, v13
	v_mul_f32_e32 v13, v15, v48
	v_rndne_f32_e32 v13, v13
	v_rndne_f32_e32 v11, v11
	v_cvt_i32_f32_e32 v13, v13
	v_cvt_i32_f32_e32 v11, v11
	v_lshrrev_b32_e32 v9, 4, v9
	v_and_b32_e32 v14, 0xf0, v14
	v_and_or_b32 v9, v9, 15, v14
	v_add_u32_e32 v14, 8, v13
	v_add_u32_e32 v15, 8, v11
	v_mul_f32_e32 v4, v4, v48
	v_mul_f32_e32 v0, v0, v48
; __device__ void phase_gather_u(const Params& p) {
;     ...
;         const int a_ = __float2int_rn(xr[m * 8 + j] * inv), b_ = __float2int_rn(xr[m * 8 + 4 + j] * inv);
;         const int ah = (a_ + 8) >> 4, bh = (b_ + 8) >> 4;
;         const int al = a_ - 16 * ah, bl = b_ - 16 * bh;
;         wh |= (((unsigned)ah & 0xfu) | (((unsigned)bh & 0xfu) << 4)) << (8 * j);
;         wl |= (((unsigned)al & 0xfu) | (((unsigned)bl & 0xfu) << 4)) << (8 * j);
;       }
;       ph[m] = wh;
;       pl[m] = wl;
;     }
;     xq[((size_t)t * 64 + lane) * 2] = ph;
;     xq[((size_t)t * 64 + lane) * 2 + 1] = pl;
;     if (lane == 0) sxa[t] = amax * (1.f / 119.f);
;     ...
; #pragma unroll 1
;   for (int r = 0; r < 4; ++r) {
; #pragma unroll 1
;     for (int t = tbase; t < T_TOK; t += tstride) {
;       const u32x4 ph = xq[((size_t)t * 64 + lane) * 2], pl = xq[((size_t)t * 64 + lane) * 2 + 1];
;       const int idA = idxg[(size_t)t * 128 + lane], idB = idxg[(size_t)t * 128 + 64 + lane];
	v_lshrrev_b32_e32 v12, 4, v12
	v_and_b32_e32 v19, 0xf0, v19
	v_lshrrev_b32_e32 v14, 4, v14
	v_and_b32_e32 v15, 0xf0, v15
	v_rndne_f32_e32 v4, v4
	v_rndne_f32_e32 v0, v0
	v_and_or_b32 v12, v12, 15, v19
	v_and_or_b32 v14, v14, 15, v15
	v_cvt_i32_f32_e32 v4, v4
	v_cvt_i32_f32_e32 v0, v0
	v_mul_f32_e32 v5, v5, v48
	v_mul_f32_e32 v1, v1, v48
	v_lshrrev_b32_e32 v55, 4, v59
	v_and_b32_e32 v56, 0xf0, v60
	v_lshrrev_b32_e32 v22, 4, v22
	v_and_b32_e32 v23, 0xf0, v23
	v_lshl_or_b32 v12, v12, 8, v18
	v_lshlrev_b32_e32 v9, 16, v9
	v_lshlrev_b32_e32 v14, 24, v14
	v_rndne_f32_e32 v5, v5
	v_rndne_f32_e32 v1, v1
	v_and_or_b32 v47, v58, s17, v47
	v_and_or_b32 v20, v55, 15, v56
	v_and_or_b32 v22, v22, 15, v23
	v_or3_b32 v18, v12, v9, v14
	v_and_b32_sdwa v9, v13, v37 dst_sel:BYTE_3 dst_unused:UNUSED_PAD src0_sel:DWORD src1_sel:DWORD
	v_cvt_i32_f32_e32 v5, v5
	v_cvt_i32_f32_e32 v1, v1
	v_lshl_or_b32 v45, v20, 8, v47
	v_lshlrev_b32_e32 v22, 24, v22
	v_lshlrev_b32_e32 v10, 16, v10
	v_lshl_or_b32 v9, v11, 28, v9
	v_or3_b32 v17, v45, v17, v22
	v_or3_b32 v22, v8, v10, v9
	v_add_u32_e32 v8, 8, v4
	v_add_u32_e32 v9, 8, v0
	v_lshlrev_b32_e32 v0, 4, v0
	v_bfe_u32 v8, v8, 4, 4
	v_and_b32_e32 v0, 0xf0, v0
	v_and_or_b32 v8, v9, s17, v8
	v_and_or_b32 v0, v4, 15, v0
	v_add_u32_e32 v4, 8, v5
	v_add_u32_e32 v9, 8, v1
	v_and_b32_e32 v5, 15, v5
	v_lshlrev_b32_e32 v1, 4, v1
	v_and_or_b32 v1, v1, s17, v5
	v_mul_f32_e32 v5, v6, v48
	v_mul_f32_e32 v2, v2, v48
	v_rndne_f32_e32 v5, v5
	v_rndne_f32_e32 v2, v2
	v_cvt_i32_f32_e32 v5, v5
	v_cvt_i32_f32_e32 v2, v2
	v_lshl_or_b32 v0, v1, 8, v0
	v_mul_f32_e32 v3, v3, v48
	v_add_u32_e32 v1, 8, v5
	v_add_u32_e32 v6, 8, v2
	v_and_b32_e32 v5, 15, v5
	v_lshlrev_b32_e32 v2, 4, v2
	v_and_or_b32 v2, v2, s17, v5
	v_mul_f32_e32 v5, v7, v48
	v_rndne_f32_e32 v5, v5
	v_rndne_f32_e32 v3, v3
	v_cvt_i32_f32_e32 v5, v5
	v_cvt_i32_f32_e32 v3, v3
	v_lshrrev_b32_e32 v1, 4, v1
	v_and_b32_e32 v6, 0xf0, v6
	v_and_or_b32 v1, v1, 15, v6
	v_add_u32_e32 v6, 8, v5
	v_add_u32_e32 v7, 8, v3
	v_lshrrev_b32_e32 v4, 4, v4
	v_and_b32_e32 v9, 0xf0, v9
	v_lshrrev_b32_e32 v6, 4, v6
	v_and_b32_e32 v7, 0xf0, v7
	v_and_or_b32 v4, v4, 15, v9
	v_and_or_b32 v6, v6, 15, v7
	v_lshl_or_b32 v4, v4, 8, v8
	v_lshlrev_b32_e32 v1, 16, v1
	v_lshlrev_b32_e32 v6, 24, v6
	v_or3_b32 v19, v4, v1, v6
	v_and_b32_sdwa v1, v5, v37 dst_sel:BYTE_3 dst_unused:UNUSED_PAD src0_sel:DWORD src1_sel:DWORD
	v_lshlrev_b32_e32 v42, 16, v42
	v_lshlrev_b32_e32 v2, 16, v2
	v_lshl_or_b32 v1, v3, 28, v1
	v_or3_b32 v20, v40, v42, v43
	v_or3_b32 v23, v0, v2, v1
	ds_write_b128 v64, v[16:19]
	ds_write_b128 v64, v[20:23] offset:16
	s_and_saveexec_b64 s[14:15], s[2:3]
	s_cbranch_execz .LBB0_1202
	v_mul_f32_e32 v0, 0x3c09ae41, v39
	global_store_dword v[24:25], v0, off
	s_branch .LBB0_1202
.LBB0_1205:
	s_or_b64 exec, exec, s[4:5]
	v_and_b32_e32 v0, 32, v139
	v_cmp_eq_u32_e64 s[2:3], 0, v0
	v_and_b32_e32 v0, 16, v139
	v_cmp_eq_u32_e64 s[4:5], 0, v0
	v_and_b32_e32 v0, 8, v139
	s_add_u32 s10, s34, 0xc000000
	v_cmp_eq_u32_e64 s[6:7], 0, v0
	v_mov_b32_e32 v1, 0
	v_lshlrev_b32_e32 v0, 5, v138
	s_addc_u32 s11, s35, 0
	s_waitcnt lgkmcnt(0)
	v_lshl_add_u64 v[2:3], s[34:35], 0, v[0:1]
	v_lshlrev_b32_e32 v0, 2, v138
	v_lshlrev_b32_e32 v82, 3, v139
	v_writelane_b32 v250, s10, 18
	v_mbcnt_hi_u32_b32 v83, -1, v30
	v_and_b32_e32 v4, 56, v82
	v_lshl_add_u64 v[76:77], s[10:11], 0, v[0:1]
	v_lshlrev_b32_e32 v0, 4, v138
	s_waitcnt vmcnt(0)
	v_lshl_add_u64 v[72:73], s[34:35], 0, v[0:1]
	v_and_b32_e32 v0, 64, v83
	s_add_u32 s70, s34, 0x17400000
	s_mov_b64 s[8:9], 0x15400000
	v_add_u32_e32 v84, 64, v0
	v_or_b32_e32 v0, v0, v4
	s_addc_u32 s71, s35, 0
	s_mov_b32 s33, 0
	v_lshl_add_u64 v[74:75], v[2:3], 0, s[8:9]
	v_writelane_b32 v250, s11, 19
	v_cmp_gt_u32_e64 s[8:9], 8, v138
	v_cmp_eq_u32_e64 s[10:11], 1, v138
	v_cmp_eq_u32_e64 s[12:13], 2, v138
	v_cmp_eq_u32_e64 s[14:15], 3, v138
	v_cmp_eq_u32_e64 s[16:17], 4, v138
	v_cmp_eq_u32_e64 s[18:19], 5, v138
	v_cmp_eq_u32_e64 s[20:21], 6, v138
	v_cmp_eq_u32_e64 s[22:23], 7, v138
	s_movk_i32 s48, 0x3fff
	v_xor_b32_e32 v89, 32, v83
	v_xor_b32_e32 v90, 16, v83
	v_xor_b32_e32 v88, 8, v83
	v_xor_b32_e32 v87, 4, v83
	v_xor_b32_e32 v86, 2, v83
	v_xor_b32_e32 v85, 1, v83
	v_lshlrev_b32_e32 v91, 2, v0
	v_and_b32_e32 v96, 15, v138
	v_lshrrev_b32_e32 v99, 4, v138
	v_lshlrev_b32_e32 v98, 2, v138
	v_lshrrev_b32_e32 v100, 6, v139
	v_cmp_eq_u32_e64 s[8:9], 0, v96
	v_lshlrev_b32_e32 v97, 5, v96
	v_lshlrev_b32_e32 v96, 4, v96
	v_readfirstlane_b32 s60, v100
	v_readfirstlane_b32 s61, v112
	s_add_u32 s64, s34, 0x15400000
	s_addc_u32 s65, s35, 0
	s_add_u32 s62, s34, 0xc000000
	s_addc_u32 s63, s35, 0
	s_lshl_b32 s60, s60, 10
	s_and_saveexec_b64 s[38:39], s[0:1]
	s_cbranch_execz .Lgu_done
	s_mov_b32 s33, 0
	s_mov_b32 s66, 0
	s_lshl_b32 s72, s60, 4
	s_add_i32 s72, s72, 0x2000
	s_lshl_b32 s40, s61, 9
	s_add_u32 s40, s62, s40
	s_addc_u32 s41, s63, 0
	global_load_dword v94, v98, s[40:41]
	global_load_dword v95, v98, s[40:41] offset:256
	s_add_i32 s37, s61, s68
	s_lshl_b32 s40, s37, 9
	s_add_u32 s40, s62, s40
	s_addc_u32 s41, s63, 0
	global_load_dword v232, v98, s[40:41]
	global_load_dword v233, v98, s[40:41] offset:256
	s_waitcnt vmcnt(2)
	s_mov_b32 s67, 0xfffffc00
